# RESID (K=1024) GEMM epilogue: all 16 residual chunks of the tile loaded up front with one wait instead of 16 serialized load+wait round trips
# speedup vs baseline: 1.0136x; 1.0136x over previous
; DI float bf2f(unsigned v) { return __uint_as_float(v << 16); }
;   DI void operator()(const f32x4 (&acc)[2][2][4][2], const pg8::Unit& u, int wr, int wc, int fr_, int fq_) const {
;     ...
;             } else if (EPI == EPI_RESID) {
;               if (n == 0) {
;                 const int f8 = u.pn * 256 + bj * 128 + wc * 32 + 8 * fq;
;                 const f32x4 v1 = acc[ai][bj][m][1];
;                 f32x4 r0, r1;
;                 if (rsrc) {
;                   r0 = *(const f32x4*)(rsrc + (size_t)token * 1024 + f8); r1 = *(const f32x4*)(rsrc + (size_t)token * 1024 + f8 + 4);
;                 } else {
;                   const u32x4 xu = *(const u32x4*)(xr + (size_t)token * 1024 + f8);
;                   r0 = (f32x4){bf2f(xu.x & 0xffffu), bf2f(xu.x >> 16), bf2f(xu.y & 0xffffu), bf2f(xu.y >> 16)};
;                   r1 = (f32x4){bf2f(xu.z & 0xffffu), bf2f(xu.z >> 16), bf2f(xu.w & 0xffffu), bf2f(xu.w >> 16)};
;                 }
;                 r0 += v; r1 += v1;
.Lrw_1644_0:
	s_waitcnt vmcnt(0)
	s_branch .LBB0_1650

; DI float bf2f(unsigned v) { return __uint_as_float(v << 16); }
;   DI void operator()(const f32x4 (&acc)[2][2][4][2], const pg8::Unit& u, int wr, int wc, int fr_, int fq_) const {
;     ...
;             } else if (EPI == EPI_RESID) {
;               if (n == 0) {
;                 const int f8 = u.pn * 256 + bj * 128 + wc * 32 + 8 * fq;
;                 const f32x4 v1 = acc[ai][bj][m][1];
;                 f32x4 r0, r1;
;                 if (rsrc) {
;                   r0 = *(const f32x4*)(rsrc + (size_t)token * 1024 + f8); r1 = *(const f32x4*)(rsrc + (size_t)token * 1024 + f8 + 4);
;                 } else {
;                   const u32x4 xu = *(const u32x4*)(xr + (size_t)token * 1024 + f8);
;                   r0 = (f32x4){bf2f(xu.x & 0xffffu), bf2f(xu.x >> 16), bf2f(xu.y & 0xffffu), bf2f(xu.y >> 16)};
;                   r1 = (f32x4){bf2f(xu.z & 0xffffu), bf2f(xu.z >> 16), bf2f(xu.w & 0xffffu), bf2f(xu.w >> 16)};
;                 }
;                 r0 += v; r1 += v1;
;                 st_bf8(xr + (size_t)token * 1024 + f8, r0, r1, 1.f);
;                 ssq += r0[0] * r0[0] + r0[1] * r0[1] + r0[2] * r0[2] + r0[3] * r0[3] + r1[0] * r1[0] + r1[1] * r1[1] + r1[2] * r1[2] + r1[3] * r1[3];
;               }
;             } else {
;               if (n == 0) {
;                 const f32x4 v1 = acc[ai][bj][m][1];
;                 u32x4 o4;
;                 { const float t0 = fmaxf(v[0], 0.f) * rinv, t1 = fmaxf(v[1], 0.f) * rinv, t2 = fmaxf(v[2], 0.f) * rinv, t3 = fmaxf(v[3], 0.f) * rinv;
;                   o4.x = pack2(t0 * t0, t1 * t1); o4.y = pack2(t2 * t2, t3 * t3); }
;                 { const float t0 = fmaxf(v1[0], 0.f) * rinv, t1 = fmaxf(v1[1], 0.f) * rinv, t2 = fmaxf(v1[2], 0.f) * rinv, t3 = fmaxf(v1[3], 0.f) * rinv;
;                   o4.z = pack2(t0 * t0, t1 * t1); o4.w = pack2(t2 * t2, t3 * t3); }
;                 *(u32x4*)((u16*)big + (size_t)token * 4096 + u.pn * 256 + bj * 128 + wc * 32 + 8 * fq) = o4;
;               }
;             }
;           }
;         if (EPI == EPI_RESID) {
;           ssq += shx(ssq, 16, t_ & 63);
;           ssq += shx(ssq, 32, t_ & 63);
;           if (fq == 0) ss_out[(size_t)token * 16 + u.pn * 4 + wc] = ssq;
.LBB0_1647:
	s_mov_b64 s[4:5], -1
	v_lshlrev_b32_e32 v250, 1, v148
	v_lshl_add_u32 v250, v150, 11, v250
	global_load_dwordx4 v[162:165], v250, s[12:13]
	global_load_dwordx4 v[166:169], v250, s[12:13] offset:256
	v_add_u32_e32 v250, 0x8000, v250
	global_load_dwordx4 v[170:173], v250, s[12:13]
	global_load_dwordx4 v[174:177], v250, s[12:13] offset:256
	v_add_u32_e32 v250, 0x8000, v250
	global_load_dwordx4 v[178:181], v250, s[12:13]
	global_load_dwordx4 v[196:199], v250, s[12:13] offset:256
	v_add_u32_e32 v250, 0x8000, v250
	global_load_dwordx4 v[200:203], v250, s[12:13]
	global_load_dwordx4 v[204:207], v250, s[12:13] offset:256
	v_add_u32_e32 v250, 0x28000, v250
	global_load_dwordx4 v[208:211], v250, s[12:13]
	global_load_dwordx4 v[212:215], v250, s[12:13] offset:256
	v_add_u32_e32 v250, 0x8000, v250
	global_load_dwordx4 v[216:219], v250, s[12:13]
	global_load_dwordx4 v[220:223], v250, s[12:13] offset:256
	v_add_u32_e32 v250, 0x8000, v250
	global_load_dwordx4 v[224:227], v250, s[12:13]
	global_load_dwordx4 v[228:231], v250, s[12:13] offset:256
	v_add_u32_e32 v250, 0x8000, v250
	global_load_dwordx4 v[232:235], v250, s[12:13]
	global_load_dwordx4 v[242:245], v250, s[12:13] offset:256
.LBB0_1648:
	v_lshlrev_b64 v[152:153], 11, v[150:151]
	v_lshl_add_u64 v[152:153], s[12:13], 0, v[152:153]
	v_readlane_b32 s51, v237, 11
	s_andn2_b64 vcc, exec, s[4:5]
	v_lshl_add_u64 v[152:153], v[148:149], 1, v[152:153]
	s_cbranch_vccnz .Lrw_1644_0
	s_waitcnt vmcnt(0)
	v_lshlrev_b32_e32 v128, 16, v162
	v_and_b32_e32 v129, 0xffff0000, v162
	v_lshlrev_b32_e32 v130, 16, v163
	v_and_b32_e32 v131, 0xffff0000, v163
	v_lshlrev_b32_e32 v132, 16, v164
	v_and_b32_e32 v133, 0xffff0000, v164
	v_lshlrev_b32_e32 v134, 16, v165
	v_and_b32_e32 v135, 0xffff0000, v165
.LBB0_1650:
	v_pk_add_f32 v[130:131], v[126:127], v[130:131]
	v_pk_add_f32 v[156:157], v[124:125], v[128:129]
	v_pk_add_f32 v[128:129], v[122:123], v[134:135]
	v_pk_add_f32 v[132:133], v[120:121], v[132:133]
	v_cvt_pk_bf16_f32 v120, v156, v157
	v_cvt_pk_bf16_f32 v121, v130, v131
	v_cvt_pk_bf16_f32 v122, v132, v133
	v_cvt_pk_bf16_f32 v123, v128, v129
	s_and_b64 vcc, exec, s[2:3]
	global_store_dwordx4 v[152:153], v[120:123], off
	s_cbranch_vccnz .LBB0_1657
	global_load_dwordx4 v[124:127], v[154:155], off offset:528
	global_load_dwordx4 v[120:123], v[154:155], off offset:512
	s_cbranch_execnz .Lrw_1644_1
.LBB0_1652:
	v_lshlrev_b32_e32 v120, 16, v166
	v_and_b32_e32 v121, 0xffff0000, v166
	v_lshlrev_b32_e32 v122, 16, v167
	v_and_b32_e32 v123, 0xffff0000, v167
	v_lshlrev_b32_e32 v124, 16, v168
	v_and_b32_e32 v125, 0xffff0000, v168
	v_lshlrev_b32_e32 v126, 16, v169
	v_and_b32_e32 v127, 0xffff0000, v169
.LBB0_1653:
	v_pk_add_f32 v[116:117], v[116:117], v[120:121]
	v_mul_f32_e32 v134, v157, v157
	v_pk_add_f32 v[118:119], v[118:119], v[122:123]
	v_pk_add_f32 v[122:123], v[112:113], v[124:125]
	v_mul_f32_e32 v112, v117, v117
	v_fmac_f32_e32 v134, v156, v156
	v_fmac_f32_e32 v112, v116, v116
	v_fmac_f32_e32 v134, v130, v130
	v_fmac_f32_e32 v112, v118, v118
	v_fmac_f32_e32 v134, v131, v131
	v_fmac_f32_e32 v112, v119, v119
	v_fmac_f32_e32 v134, v132, v132
	v_fmac_f32_e32 v112, v122, v122
	v_fmac_f32_e32 v134, v133, v133
	v_pk_add_f32 v[120:121], v[114:115], v[126:127]
	v_fmac_f32_e32 v112, v123, v123
	v_fmac_f32_e32 v134, v128, v128
	v_fmac_f32_e32 v112, v120, v120
	v_fmac_f32_e32 v134, v129, v129
	v_lshlrev_b32_e32 v128, 2, v161
	v_fmac_f32_e32 v112, v121, v121
	v_bitop3_b32 v129, v128, 64, v190 bitop3:0x6c
	v_add_f32_e32 v112, v134, v112
	ds_bpermute_b32 v113, v129, v112
	s_movk_i32 s4, 0x80
	v_bitop3_b32 v128, v128, s4, v190 bitop3:0x6c
	s_lshl_b32 s28, s24, 2
	v_cmp_eq_u32_e64 s[4:5], 0, v160
	s_waitcnt lgkmcnt(0)
	v_add_f32_e32 v112, v112, v113
	ds_bpermute_b32 v113, v128, v112
	s_ashr_i32 s29, s28, 31
	v_cvt_pk_bf16_f32 v114, v116, v117
	v_cvt_pk_bf16_f32 v115, v118, v119
	v_cvt_pk_bf16_f32 v116, v122, v123
	v_cvt_pk_bf16_f32 v117, v120, v121
	global_store_dwordx4 v[152:153], v[114:117], off offset:256
	s_and_saveexec_b64 s[34:35], s[4:5]
	s_cbranch_execz .LBB0_1655
	s_waitcnt lgkmcnt(0)
	v_add_f32_e32 v114, v112, v113
	v_lshlrev_b64 v[112:113], 6, v[150:151]
	v_lshl_add_u64 v[112:113], s[10:11], 0, v[112:113]
	v_lshl_add_u64 v[112:113], s[28:29], 2, v[112:113]
	s_lshl_b32 s24, s46, 2
	v_lshl_add_u64 v[112:113], v[112:113], 0, s[24:25]
	global_store_dword v[112:113], v114, off

; DI float bf2f(unsigned v) { return __uint_as_float(v << 16); }
;   DI void operator()(const f32x4 (&acc)[2][2][4][2], const pg8::Unit& u, int wr, int wc, int fr_, int fq_) const {
;     ...
;             } else if (EPI == EPI_RESID) {
;               if (n == 0) {
;                 const int f8 = u.pn * 256 + bj * 128 + wc * 32 + 8 * fq;
;                 const f32x4 v1 = acc[ai][bj][m][1];
;                 f32x4 r0, r1;
;                 if (rsrc) {
;                   r0 = *(const f32x4*)(rsrc + (size_t)token * 1024 + f8); r1 = *(const f32x4*)(rsrc + (size_t)token * 1024 + f8 + 4);
;                 } else {
;                   const u32x4 xu = *(const u32x4*)(xr + (size_t)token * 1024 + f8);
;                   r0 = (f32x4){bf2f(xu.x & 0xffffu), bf2f(xu.x >> 16), bf2f(xu.y & 0xffffu), bf2f(xu.y >> 16)};
;                   r1 = (f32x4){bf2f(xu.z & 0xffffu), bf2f(xu.z >> 16), bf2f(xu.w & 0xffffu), bf2f(xu.w >> 16)};
;                 }
;                 r0 += v; r1 += v1;
;                 st_bf8(xr + (size_t)token * 1024 + f8, r0, r1, 1.f);
;                 ssq += r0[0] * r0[0] + r0[1] * r0[1] + r0[2] * r0[2] + r0[3] * r0[3] + r1[0] * r1[0] + r1[1] * r1[1] + r1[2] * r1[2] + r1[3] * r1[3];
;               }
;             } else {
;               if (n == 0) {
;                 const f32x4 v1 = acc[ai][bj][m][1];
;                 u32x4 o4;
;                 { const float t0 = fmaxf(v[0], 0.f) * rinv, t1 = fmaxf(v[1], 0.f) * rinv, t2 = fmaxf(v[2], 0.f) * rinv, t3 = fmaxf(v[3], 0.f) * rinv;
;                   o4.x = pack2(t0 * t0, t1 * t1); o4.y = pack2(t2 * t2, t3 * t3); }
;                 { const float t0 = fmaxf(v1[0], 0.f) * rinv, t1 = fmaxf(v1[1], 0.f) * rinv, t2 = fmaxf(v1[2], 0.f) * rinv, t3 = fmaxf(v1[3], 0.f) * rinv;
;                   o4.z = pack2(t0 * t0, t1 * t1); o4.w = pack2(t2 * t2, t3 * t3); }
;                 *(u32x4*)((u16*)big + (size_t)token * 4096 + u.pn * 256 + bj * 128 + wc * 32 + 8 * fq) = o4;
;               }
;             }
;           }
;         if (EPI == EPI_RESID) {
;           ssq += shx(ssq, 16, t_ & 63);
;           ssq += shx(ssq, 32, t_ & 63);
;           if (fq == 0) ss_out[(size_t)token * 16 + u.pn * 4 + wc] = ssq;
.LBB0_1659:
	v_lshlrev_b64 v[122:123], 11, v[120:121]
	v_lshl_add_u64 v[122:123], s[12:13], 0, v[122:123]
	s_andn2_b64 vcc, exec, s[34:35]
	v_lshl_add_u64 v[122:123], v[148:149], 1, v[122:123]
	s_cbranch_vccnz .Lrw_1644_2
	v_lshlrev_b32_e32 v112, 16, v170
	v_and_b32_e32 v113, 0xffff0000, v170
	v_lshlrev_b32_e32 v114, 16, v171
	v_and_b32_e32 v115, 0xffff0000, v171
	v_lshlrev_b32_e32 v116, 16, v172
	v_and_b32_e32 v117, 0xffff0000, v172
	v_lshlrev_b32_e32 v118, 16, v173
	v_and_b32_e32 v119, 0xffff0000, v173
.LBB0_1661:
	v_pk_add_f32 v[114:115], v[110:111], v[114:115]
	v_pk_add_f32 v[126:127], v[108:109], v[112:113]
	v_pk_add_f32 v[112:113], v[106:107], v[118:119]
	v_pk_add_f32 v[116:117], v[104:105], v[116:117]
	v_cvt_pk_bf16_f32 v104, v126, v127
	v_cvt_pk_bf16_f32 v105, v114, v115
	v_cvt_pk_bf16_f32 v106, v116, v117
	v_cvt_pk_bf16_f32 v107, v112, v113
	s_and_b64 vcc, exec, s[2:3]
	global_store_dwordx4 v[122:123], v[104:107], off
	s_cbranch_vccnz .LBB0_1668
	global_load_dwordx4 v[108:111], v[124:125], off offset:528
	global_load_dwordx4 v[104:107], v[124:125], off offset:512
	s_cbranch_execnz .Lrw_1644_3
.LBB0_1663:
	v_lshlrev_b32_e32 v104, 16, v174
	v_and_b32_e32 v105, 0xffff0000, v174
	v_lshlrev_b32_e32 v106, 16, v175
	v_and_b32_e32 v107, 0xffff0000, v175
	v_lshlrev_b32_e32 v108, 16, v176
	v_and_b32_e32 v109, 0xffff0000, v176
	v_lshlrev_b32_e32 v110, 16, v177
	v_and_b32_e32 v111, 0xffff0000, v177
.LBB0_1664:
	v_pk_add_f32 v[100:101], v[100:101], v[104:105]
	v_mul_f32_e32 v118, v127, v127
	v_pk_add_f32 v[102:103], v[102:103], v[106:107]
	v_pk_add_f32 v[106:107], v[96:97], v[108:109]
	v_mul_f32_e32 v96, v101, v101
	v_fmac_f32_e32 v118, v126, v126
	v_fmac_f32_e32 v96, v100, v100
	v_fmac_f32_e32 v118, v114, v114
	v_fmac_f32_e32 v96, v102, v102
	v_fmac_f32_e32 v118, v115, v115
	v_fmac_f32_e32 v96, v103, v103
	v_fmac_f32_e32 v118, v116, v116
	v_fmac_f32_e32 v96, v106, v106
	v_fmac_f32_e32 v118, v117, v117
	v_pk_add_f32 v[104:105], v[98:99], v[110:111]
	v_fmac_f32_e32 v96, v107, v107
	v_fmac_f32_e32 v118, v112, v112
	v_fmac_f32_e32 v96, v104, v104
	v_fmac_f32_e32 v118, v113, v113
	v_fmac_f32_e32 v96, v105, v105
	v_add_f32_e32 v96, v118, v96
	ds_bpermute_b32 v97, v129, v96
	v_cvt_pk_bf16_f32 v98, v100, v101
	v_cvt_pk_bf16_f32 v99, v102, v103
	v_cvt_pk_bf16_f32 v100, v106, v107
	v_cvt_pk_bf16_f32 v101, v104, v105
	s_waitcnt lgkmcnt(0)
	v_add_f32_e32 v96, v96, v97
	ds_bpermute_b32 v97, v128, v96
	global_store_dwordx4 v[122:123], v[98:101], off offset:256
	s_and_saveexec_b64 s[34:35], s[4:5]
	s_cbranch_execz .LBB0_1666
	s_waitcnt lgkmcnt(0)
	v_add_f32_e32 v98, v96, v97
	v_lshlrev_b64 v[96:97], 6, v[120:121]
	v_lshl_add_u64 v[96:97], s[10:11], 0, v[96:97]
	v_lshl_add_u64 v[96:97], s[28:29], 2, v[96:97]
	s_lshl_b32 s24, s46, 2
	v_lshl_add_u64 v[96:97], v[96:97], 0, s[24:25]
	global_store_dword v[96:97], v98, off

; DI float bf2f(unsigned v) { return __uint_as_float(v << 16); }
;   DI void operator()(const f32x4 (&acc)[2][2][4][2], const pg8::Unit& u, int wr, int wc, int fr_, int fq_) const {
;     ...
;             } else if (EPI == EPI_RESID) {
;               if (n == 0) {
;                 const int f8 = u.pn * 256 + bj * 128 + wc * 32 + 8 * fq;
;                 const f32x4 v1 = acc[ai][bj][m][1];
;                 f32x4 r0, r1;
;                 if (rsrc) {
;                   r0 = *(const f32x4*)(rsrc + (size_t)token * 1024 + f8); r1 = *(const f32x4*)(rsrc + (size_t)token * 1024 + f8 + 4);
;                 } else {
;                   const u32x4 xu = *(const u32x4*)(xr + (size_t)token * 1024 + f8);
;                   r0 = (f32x4){bf2f(xu.x & 0xffffu), bf2f(xu.x >> 16), bf2f(xu.y & 0xffffu), bf2f(xu.y >> 16)};
;                   r1 = (f32x4){bf2f(xu.z & 0xffffu), bf2f(xu.z >> 16), bf2f(xu.w & 0xffffu), bf2f(xu.w >> 16)};
;                 }
;                 r0 += v; r1 += v1;
;                 st_bf8(xr + (size_t)token * 1024 + f8, r0, r1, 1.f);
;                 ssq += r0[0] * r0[0] + r0[1] * r0[1] + r0[2] * r0[2] + r0[3] * r0[3] + r1[0] * r1[0] + r1[1] * r1[1] + r1[2] * r1[2] + r1[3] * r1[3];
;               }
;             } else {
;               if (n == 0) {
;                 const f32x4 v1 = acc[ai][bj][m][1];
;                 u32x4 o4;
;                 { const float t0 = fmaxf(v[0], 0.f) * rinv, t1 = fmaxf(v[1], 0.f) * rinv, t2 = fmaxf(v[2], 0.f) * rinv, t3 = fmaxf(v[3], 0.f) * rinv;
;                   o4.x = pack2(t0 * t0, t1 * t1); o4.y = pack2(t2 * t2, t3 * t3); }
;                 { const float t0 = fmaxf(v1[0], 0.f) * rinv, t1 = fmaxf(v1[1], 0.f) * rinv, t2 = fmaxf(v1[2], 0.f) * rinv, t3 = fmaxf(v1[3], 0.f) * rinv;
;                   o4.z = pack2(t0 * t0, t1 * t1); o4.w = pack2(t2 * t2, t3 * t3); }
;                 *(u32x4*)((u16*)big + (size_t)token * 4096 + u.pn * 256 + bj * 128 + wc * 32 + 8 * fq) = o4;
;               }
;             }
;           }
;         if (EPI == EPI_RESID) {
;           ssq += shx(ssq, 16, t_ & 63);
;           ssq += shx(ssq, 32, t_ & 63);
;           if (fq == 0) ss_out[(size_t)token * 16 + u.pn * 4 + wc] = ssq;
.LBB0_1670:
	v_lshlrev_b64 v[106:107], 11, v[104:105]
	v_lshl_add_u64 v[106:107], s[12:13], 0, v[106:107]
	s_andn2_b64 vcc, exec, s[34:35]
	v_lshl_add_u64 v[106:107], v[148:149], 1, v[106:107]
	s_cbranch_vccnz .Lrw_1644_4
	v_lshlrev_b32_e32 v96, 16, v178
	v_and_b32_e32 v97, 0xffff0000, v178
	v_lshlrev_b32_e32 v98, 16, v179
	v_and_b32_e32 v99, 0xffff0000, v179
	v_lshlrev_b32_e32 v100, 16, v180
	v_and_b32_e32 v101, 0xffff0000, v180
	v_lshlrev_b32_e32 v102, 16, v181
	v_and_b32_e32 v103, 0xffff0000, v181
.LBB0_1672:
	v_pk_add_f32 v[98:99], v[94:95], v[98:99]
	v_pk_add_f32 v[110:111], v[92:93], v[96:97]
	v_pk_add_f32 v[96:97], v[90:91], v[102:103]
	v_pk_add_f32 v[100:101], v[88:89], v[100:101]
	v_cvt_pk_bf16_f32 v88, v110, v111
	v_cvt_pk_bf16_f32 v89, v98, v99
	v_cvt_pk_bf16_f32 v90, v100, v101
	v_cvt_pk_bf16_f32 v91, v96, v97
	s_and_b64 vcc, exec, s[2:3]
	global_store_dwordx4 v[106:107], v[88:91], off
	s_cbranch_vccnz .LBB0_1679
	global_load_dwordx4 v[92:95], v[108:109], off offset:528
	global_load_dwordx4 v[88:91], v[108:109], off offset:512
	s_cbranch_execnz .Lrw_1644_5
.LBB0_1674:
	v_lshlrev_b32_e32 v88, 16, v196
	v_and_b32_e32 v89, 0xffff0000, v196
	v_lshlrev_b32_e32 v90, 16, v197
	v_and_b32_e32 v91, 0xffff0000, v197
	v_lshlrev_b32_e32 v92, 16, v198
	v_and_b32_e32 v93, 0xffff0000, v198
	v_lshlrev_b32_e32 v94, 16, v199
	v_and_b32_e32 v95, 0xffff0000, v199
.LBB0_1675:
	v_pk_add_f32 v[84:85], v[84:85], v[88:89]
	v_mul_f32_e32 v102, v111, v111
	v_pk_add_f32 v[86:87], v[86:87], v[90:91]
	v_pk_add_f32 v[90:91], v[80:81], v[92:93]
	v_mul_f32_e32 v80, v85, v85
	v_fmac_f32_e32 v102, v110, v110
	v_fmac_f32_e32 v80, v84, v84
	v_fmac_f32_e32 v102, v98, v98
	v_fmac_f32_e32 v80, v86, v86
	v_fmac_f32_e32 v102, v99, v99
	v_fmac_f32_e32 v80, v87, v87
	v_fmac_f32_e32 v102, v100, v100
	v_fmac_f32_e32 v80, v90, v90
	v_fmac_f32_e32 v102, v101, v101
	v_pk_add_f32 v[88:89], v[82:83], v[94:95]
	v_fmac_f32_e32 v80, v91, v91
	v_fmac_f32_e32 v102, v96, v96
	v_fmac_f32_e32 v80, v88, v88
	v_fmac_f32_e32 v102, v97, v97
	v_fmac_f32_e32 v80, v89, v89
	v_add_f32_e32 v80, v102, v80
	ds_bpermute_b32 v81, v129, v80
	v_cvt_pk_bf16_f32 v82, v84, v85
	v_cvt_pk_bf16_f32 v83, v86, v87
	v_cvt_pk_bf16_f32 v84, v90, v91
	v_cvt_pk_bf16_f32 v85, v88, v89
	s_waitcnt lgkmcnt(0)
	v_add_f32_e32 v80, v80, v81
	ds_bpermute_b32 v81, v128, v80
	global_store_dwordx4 v[106:107], v[82:85], off offset:256
	s_and_saveexec_b64 s[34:35], s[4:5]
	s_cbranch_execz .LBB0_1677
	s_waitcnt lgkmcnt(0)
	v_add_f32_e32 v82, v80, v81
	v_lshlrev_b64 v[80:81], 6, v[104:105]
	v_lshl_add_u64 v[80:81], s[10:11], 0, v[80:81]
	v_lshl_add_u64 v[80:81], s[28:29], 2, v[80:81]
	s_lshl_b32 s24, s46, 2
	v_lshl_add_u64 v[80:81], v[80:81], 0, s[24:25]
	global_store_dword v[80:81], v82, off

; DI float bf2f(unsigned v) { return __uint_as_float(v << 16); }
;   DI void operator()(const f32x4 (&acc)[2][2][4][2], const pg8::Unit& u, int wr, int wc, int fr_, int fq_) const {
;     ...
;             } else if (EPI == EPI_RESID) {
;               if (n == 0) {
;                 const int f8 = u.pn * 256 + bj * 128 + wc * 32 + 8 * fq;
;                 const f32x4 v1 = acc[ai][bj][m][1];
;                 f32x4 r0, r1;
;                 if (rsrc) {
;                   r0 = *(const f32x4*)(rsrc + (size_t)token * 1024 + f8); r1 = *(const f32x4*)(rsrc + (size_t)token * 1024 + f8 + 4);
;                 } else {
;                   const u32x4 xu = *(const u32x4*)(xr + (size_t)token * 1024 + f8);
;                   r0 = (f32x4){bf2f(xu.x & 0xffffu), bf2f(xu.x >> 16), bf2f(xu.y & 0xffffu), bf2f(xu.y >> 16)};
;                   r1 = (f32x4){bf2f(xu.z & 0xffffu), bf2f(xu.z >> 16), bf2f(xu.w & 0xffffu), bf2f(xu.w >> 16)};
;                 }
;                 r0 += v; r1 += v1;
;                 st_bf8(xr + (size_t)token * 1024 + f8, r0, r1, 1.f);
;                 ssq += r0[0] * r0[0] + r0[1] * r0[1] + r0[2] * r0[2] + r0[3] * r0[3] + r1[0] * r1[0] + r1[1] * r1[1] + r1[2] * r1[2] + r1[3] * r1[3];
;               }
;             } else {
;               if (n == 0) {
;                 const f32x4 v1 = acc[ai][bj][m][1];
;                 u32x4 o4;
;                 { const float t0 = fmaxf(v[0], 0.f) * rinv, t1 = fmaxf(v[1], 0.f) * rinv, t2 = fmaxf(v[2], 0.f) * rinv, t3 = fmaxf(v[3], 0.f) * rinv;
;                   o4.x = pack2(t0 * t0, t1 * t1); o4.y = pack2(t2 * t2, t3 * t3); }
;                 { const float t0 = fmaxf(v1[0], 0.f) * rinv, t1 = fmaxf(v1[1], 0.f) * rinv, t2 = fmaxf(v1[2], 0.f) * rinv, t3 = fmaxf(v1[3], 0.f) * rinv;
;                   o4.z = pack2(t0 * t0, t1 * t1); o4.w = pack2(t2 * t2, t3 * t3); }
;                 *(u32x4*)((u16*)big + (size_t)token * 4096 + u.pn * 256 + bj * 128 + wc * 32 + 8 * fq) = o4;
;               }
;             }
;           }
;         if (EPI == EPI_RESID) {
;           ssq += shx(ssq, 16, t_ & 63);
;           ssq += shx(ssq, 32, t_ & 63);
;           if (fq == 0) ss_out[(size_t)token * 16 + u.pn * 4 + wc] = ssq;
.LBB0_1681:
	v_lshlrev_b64 v[90:91], 11, v[88:89]
	v_lshl_add_u64 v[90:91], s[12:13], 0, v[90:91]
	s_andn2_b64 vcc, exec, s[34:35]
	v_lshl_add_u64 v[90:91], v[148:149], 1, v[90:91]
	s_cbranch_vccnz .Lrw_1644_6
	v_lshlrev_b32_e32 v80, 16, v200
	v_and_b32_e32 v81, 0xffff0000, v200
	v_lshlrev_b32_e32 v82, 16, v201
	v_and_b32_e32 v83, 0xffff0000, v201
	v_lshlrev_b32_e32 v84, 16, v202
	v_and_b32_e32 v85, 0xffff0000, v202
	v_lshlrev_b32_e32 v86, 16, v203
	v_and_b32_e32 v87, 0xffff0000, v203
.LBB0_1683:
	v_pk_add_f32 v[82:83], v[78:79], v[82:83]
	v_pk_add_f32 v[94:95], v[76:77], v[80:81]
	v_pk_add_f32 v[80:81], v[74:75], v[86:87]
	v_pk_add_f32 v[84:85], v[72:73], v[84:85]
	v_cvt_pk_bf16_f32 v72, v94, v95
	v_cvt_pk_bf16_f32 v73, v82, v83
	v_cvt_pk_bf16_f32 v74, v84, v85
	v_cvt_pk_bf16_f32 v75, v80, v81
	s_and_b64 vcc, exec, s[2:3]
	global_store_dwordx4 v[90:91], v[72:75], off
	s_cbranch_vccnz .LBB0_1690
	global_load_dwordx4 v[76:79], v[92:93], off offset:528
	global_load_dwordx4 v[72:75], v[92:93], off offset:512
	s_cbranch_execnz .Lrw_1644_7
.LBB0_1685:
	v_lshlrev_b32_e32 v72, 16, v204
	v_and_b32_e32 v73, 0xffff0000, v204
	v_lshlrev_b32_e32 v74, 16, v205
	v_and_b32_e32 v75, 0xffff0000, v205
	v_lshlrev_b32_e32 v76, 16, v206
	v_and_b32_e32 v77, 0xffff0000, v206
	v_lshlrev_b32_e32 v78, 16, v207
	v_and_b32_e32 v79, 0xffff0000, v207
.LBB0_1686:
	v_pk_add_f32 v[68:69], v[68:69], v[72:73]
	v_mul_f32_e32 v86, v95, v95
	v_pk_add_f32 v[70:71], v[70:71], v[74:75]
	v_pk_add_f32 v[74:75], v[64:65], v[76:77]
	v_mul_f32_e32 v64, v69, v69
	v_fmac_f32_e32 v86, v94, v94
	v_fmac_f32_e32 v64, v68, v68
	v_fmac_f32_e32 v86, v82, v82
	v_fmac_f32_e32 v64, v70, v70
	v_fmac_f32_e32 v86, v83, v83
	v_fmac_f32_e32 v64, v71, v71
	v_fmac_f32_e32 v86, v84, v84
	v_fmac_f32_e32 v64, v74, v74
	v_fmac_f32_e32 v86, v85, v85
	v_pk_add_f32 v[72:73], v[66:67], v[78:79]
	v_fmac_f32_e32 v64, v75, v75
	v_fmac_f32_e32 v86, v80, v80
	v_fmac_f32_e32 v64, v72, v72
	v_fmac_f32_e32 v86, v81, v81
	v_fmac_f32_e32 v64, v73, v73
	v_add_f32_e32 v64, v86, v64
	ds_bpermute_b32 v65, v129, v64
	v_cvt_pk_bf16_f32 v66, v68, v69
	v_cvt_pk_bf16_f32 v67, v70, v71
	v_cvt_pk_bf16_f32 v68, v74, v75
	v_cvt_pk_bf16_f32 v69, v72, v73
	s_waitcnt lgkmcnt(0)
	v_add_f32_e32 v64, v64, v65
	ds_bpermute_b32 v65, v128, v64
	global_store_dwordx4 v[90:91], v[66:69], off offset:256
	s_and_saveexec_b64 s[34:35], s[4:5]
	s_cbranch_execz .LBB0_1688
	s_waitcnt lgkmcnt(0)
	v_add_f32_e32 v66, v64, v65
	v_lshlrev_b64 v[64:65], 6, v[88:89]
	v_lshl_add_u64 v[64:65], s[10:11], 0, v[64:65]
	v_lshl_add_u64 v[64:65], s[28:29], 2, v[64:65]
	s_lshl_b32 s24, s46, 2
	v_lshl_add_u64 v[64:65], v[64:65], 0, s[24:25]
	global_store_dword v[64:65], v66, off

; DI float bf2f(unsigned v) { return __uint_as_float(v << 16); }
;   DI void operator()(const f32x4 (&acc)[2][2][4][2], const pg8::Unit& u, int wr, int wc, int fr_, int fq_) const {
;     ...
;             } else if (EPI == EPI_RESID) {
;               if (n == 0) {
;                 const int f8 = u.pn * 256 + bj * 128 + wc * 32 + 8 * fq;
;                 const f32x4 v1 = acc[ai][bj][m][1];
;                 f32x4 r0, r1;
;                 if (rsrc) {
;                   r0 = *(const f32x4*)(rsrc + (size_t)token * 1024 + f8); r1 = *(const f32x4*)(rsrc + (size_t)token * 1024 + f8 + 4);
;                 } else {
;                   const u32x4 xu = *(const u32x4*)(xr + (size_t)token * 1024 + f8);
;                   r0 = (f32x4){bf2f(xu.x & 0xffffu), bf2f(xu.x >> 16), bf2f(xu.y & 0xffffu), bf2f(xu.y >> 16)};
;                   r1 = (f32x4){bf2f(xu.z & 0xffffu), bf2f(xu.z >> 16), bf2f(xu.w & 0xffffu), bf2f(xu.w >> 16)};
;                 }
;                 r0 += v; r1 += v1;
;                 st_bf8(xr + (size_t)token * 1024 + f8, r0, r1, 1.f);
;                 ssq += r0[0] * r0[0] + r0[1] * r0[1] + r0[2] * r0[2] + r0[3] * r0[3] + r1[0] * r1[0] + r1[1] * r1[1] + r1[2] * r1[2] + r1[3] * r1[3];
;               }
;             } else {
;               if (n == 0) {
;                 const f32x4 v1 = acc[ai][bj][m][1];
;                 u32x4 o4;
;                 { const float t0 = fmaxf(v[0], 0.f) * rinv, t1 = fmaxf(v[1], 0.f) * rinv, t2 = fmaxf(v[2], 0.f) * rinv, t3 = fmaxf(v[3], 0.f) * rinv;
;                   o4.x = pack2(t0 * t0, t1 * t1); o4.y = pack2(t2 * t2, t3 * t3); }
;                 { const float t0 = fmaxf(v1[0], 0.f) * rinv, t1 = fmaxf(v1[1], 0.f) * rinv, t2 = fmaxf(v1[2], 0.f) * rinv, t3 = fmaxf(v1[3], 0.f) * rinv;
;                   o4.z = pack2(t0 * t0, t1 * t1); o4.w = pack2(t2 * t2, t3 * t3); }
;                 *(u32x4*)((u16*)big + (size_t)token * 4096 + u.pn * 256 + bj * 128 + wc * 32 + 8 * fq) = o4;
;               }
;             }
;           }
;         if (EPI == EPI_RESID) {
;           ssq += shx(ssq, 16, t_ & 63);
;           ssq += shx(ssq, 32, t_ & 63);
;           if (fq == 0) ss_out[(size_t)token * 16 + u.pn * 4 + wc] = ssq;
.LBB0_1692:
	v_lshlrev_b64 v[74:75], 11, v[72:73]
	v_lshl_add_u64 v[74:75], s[12:13], 0, v[74:75]
	s_andn2_b64 vcc, exec, s[34:35]
	v_lshl_add_u64 v[74:75], v[148:149], 1, v[74:75]
	s_cbranch_vccnz .Lrw_1644_8
	v_lshlrev_b32_e32 v64, 16, v208
	v_and_b32_e32 v65, 0xffff0000, v208
	v_lshlrev_b32_e32 v66, 16, v209
	v_and_b32_e32 v67, 0xffff0000, v209
	v_lshlrev_b32_e32 v68, 16, v210
	v_and_b32_e32 v69, 0xffff0000, v210
	v_lshlrev_b32_e32 v70, 16, v211
	v_and_b32_e32 v71, 0xffff0000, v211
.LBB0_1694:
	v_pk_add_f32 v[66:67], v[62:63], v[66:67]
	v_pk_add_f32 v[78:79], v[60:61], v[64:65]
	v_pk_add_f32 v[64:65], v[58:59], v[70:71]
	v_pk_add_f32 v[68:69], v[56:57], v[68:69]
	v_cvt_pk_bf16_f32 v56, v78, v79
	v_cvt_pk_bf16_f32 v57, v66, v67
	v_cvt_pk_bf16_f32 v58, v68, v69
	v_cvt_pk_bf16_f32 v59, v64, v65
	s_and_b64 vcc, exec, s[2:3]
	global_store_dwordx4 v[74:75], v[56:59], off
	s_cbranch_vccnz .LBB0_1701
	global_load_dwordx4 v[60:63], v[76:77], off offset:528
	global_load_dwordx4 v[56:59], v[76:77], off offset:512
	s_cbranch_execnz .Lrw_1644_9
.LBB0_1696:
	v_lshlrev_b32_e32 v56, 16, v212
	v_and_b32_e32 v57, 0xffff0000, v212
	v_lshlrev_b32_e32 v58, 16, v213
	v_and_b32_e32 v59, 0xffff0000, v213
	v_lshlrev_b32_e32 v60, 16, v214
	v_and_b32_e32 v61, 0xffff0000, v214
	v_lshlrev_b32_e32 v62, 16, v215
	v_and_b32_e32 v63, 0xffff0000, v215
.LBB0_1697:
	v_pk_add_f32 v[52:53], v[52:53], v[56:57]
	v_mul_f32_e32 v70, v79, v79
	v_pk_add_f32 v[54:55], v[54:55], v[58:59]
	v_pk_add_f32 v[58:59], v[48:49], v[60:61]
	v_mul_f32_e32 v48, v53, v53
	v_fmac_f32_e32 v70, v78, v78
	v_fmac_f32_e32 v48, v52, v52
	v_fmac_f32_e32 v70, v66, v66
	v_fmac_f32_e32 v48, v54, v54
	v_fmac_f32_e32 v70, v67, v67
	v_fmac_f32_e32 v48, v55, v55
	v_fmac_f32_e32 v70, v68, v68
	v_fmac_f32_e32 v48, v58, v58
	v_fmac_f32_e32 v70, v69, v69
	v_pk_add_f32 v[56:57], v[50:51], v[62:63]
	v_fmac_f32_e32 v48, v59, v59
	v_fmac_f32_e32 v70, v64, v64
	v_fmac_f32_e32 v48, v56, v56
	v_fmac_f32_e32 v70, v65, v65
	v_fmac_f32_e32 v48, v57, v57
	v_add_f32_e32 v48, v70, v48
	ds_bpermute_b32 v49, v129, v48
	v_cvt_pk_bf16_f32 v50, v52, v53
	v_cvt_pk_bf16_f32 v51, v54, v55
	v_cvt_pk_bf16_f32 v52, v58, v59
	v_cvt_pk_bf16_f32 v53, v56, v57
	s_waitcnt lgkmcnt(0)
	v_add_f32_e32 v48, v48, v49
	ds_bpermute_b32 v49, v128, v48
	global_store_dwordx4 v[74:75], v[50:53], off offset:256
	s_and_saveexec_b64 s[34:35], s[4:5]
	s_cbranch_execz .LBB0_1699
	s_waitcnt lgkmcnt(0)
	v_add_f32_e32 v50, v48, v49
	v_lshlrev_b64 v[48:49], 6, v[72:73]
	v_lshl_add_u64 v[48:49], s[10:11], 0, v[48:49]
	v_lshl_add_u64 v[48:49], s[28:29], 2, v[48:49]
	s_lshl_b32 s24, s46, 2
	v_lshl_add_u64 v[48:49], v[48:49], 0, s[24:25]
	global_store_dword v[48:49], v50, off

; DI float bf2f(unsigned v) { return __uint_as_float(v << 16); }
;   DI void operator()(const f32x4 (&acc)[2][2][4][2], const pg8::Unit& u, int wr, int wc, int fr_, int fq_) const {
;     ...
;             } else if (EPI == EPI_RESID) {
;               if (n == 0) {
;                 const int f8 = u.pn * 256 + bj * 128 + wc * 32 + 8 * fq;
;                 const f32x4 v1 = acc[ai][bj][m][1];
;                 f32x4 r0, r1;
;                 if (rsrc) {
;                   r0 = *(const f32x4*)(rsrc + (size_t)token * 1024 + f8); r1 = *(const f32x4*)(rsrc + (size_t)token * 1024 + f8 + 4);
;                 } else {
;                   const u32x4 xu = *(const u32x4*)(xr + (size_t)token * 1024 + f8);
;                   r0 = (f32x4){bf2f(xu.x & 0xffffu), bf2f(xu.x >> 16), bf2f(xu.y & 0xffffu), bf2f(xu.y >> 16)};
;                   r1 = (f32x4){bf2f(xu.z & 0xffffu), bf2f(xu.z >> 16), bf2f(xu.w & 0xffffu), bf2f(xu.w >> 16)};
;                 }
;                 r0 += v; r1 += v1;
;                 st_bf8(xr + (size_t)token * 1024 + f8, r0, r1, 1.f);
;                 ssq += r0[0] * r0[0] + r0[1] * r0[1] + r0[2] * r0[2] + r0[3] * r0[3] + r1[0] * r1[0] + r1[1] * r1[1] + r1[2] * r1[2] + r1[3] * r1[3];
;               }
;             } else {
;               if (n == 0) {
;                 const f32x4 v1 = acc[ai][bj][m][1];
;                 u32x4 o4;
;                 { const float t0 = fmaxf(v[0], 0.f) * rinv, t1 = fmaxf(v[1], 0.f) * rinv, t2 = fmaxf(v[2], 0.f) * rinv, t3 = fmaxf(v[3], 0.f) * rinv;
;                   o4.x = pack2(t0 * t0, t1 * t1); o4.y = pack2(t2 * t2, t3 * t3); }
;                 { const float t0 = fmaxf(v1[0], 0.f) * rinv, t1 = fmaxf(v1[1], 0.f) * rinv, t2 = fmaxf(v1[2], 0.f) * rinv, t3 = fmaxf(v1[3], 0.f) * rinv;
;                   o4.z = pack2(t0 * t0, t1 * t1); o4.w = pack2(t2 * t2, t3 * t3); }
;                 *(u32x4*)((u16*)big + (size_t)token * 4096 + u.pn * 256 + bj * 128 + wc * 32 + 8 * fq) = o4;
;               }
;             }
;           }
;         if (EPI == EPI_RESID) {
;           ssq += shx(ssq, 16, t_ & 63);
;           ssq += shx(ssq, 32, t_ & 63);
;           if (fq == 0) ss_out[(size_t)token * 16 + u.pn * 4 + wc] = ssq;
.LBB0_1703:
	v_lshlrev_b64 v[58:59], 11, v[56:57]
	v_lshl_add_u64 v[58:59], s[12:13], 0, v[58:59]
	s_andn2_b64 vcc, exec, s[34:35]
	v_lshl_add_u64 v[58:59], v[148:149], 1, v[58:59]
	s_cbranch_vccnz .Lrw_1644_10
	v_lshlrev_b32_e32 v48, 16, v216
	v_and_b32_e32 v49, 0xffff0000, v216
	v_lshlrev_b32_e32 v50, 16, v217
	v_and_b32_e32 v51, 0xffff0000, v217
	v_lshlrev_b32_e32 v52, 16, v218
	v_and_b32_e32 v53, 0xffff0000, v218
	v_lshlrev_b32_e32 v54, 16, v219
	v_and_b32_e32 v55, 0xffff0000, v219
.LBB0_1705:
	v_pk_add_f32 v[50:51], v[46:47], v[50:51]
	v_pk_add_f32 v[62:63], v[44:45], v[48:49]
	v_pk_add_f32 v[48:49], v[42:43], v[54:55]
	v_pk_add_f32 v[52:53], v[40:41], v[52:53]
	v_cvt_pk_bf16_f32 v40, v62, v63
	v_cvt_pk_bf16_f32 v41, v50, v51
	v_cvt_pk_bf16_f32 v42, v52, v53
	v_cvt_pk_bf16_f32 v43, v48, v49
	s_and_b64 vcc, exec, s[2:3]
	global_store_dwordx4 v[58:59], v[40:43], off
	s_cbranch_vccnz .LBB0_1712
	global_load_dwordx4 v[44:47], v[60:61], off offset:528
	global_load_dwordx4 v[40:43], v[60:61], off offset:512
	s_cbranch_execnz .Lrw_1644_11
.LBB0_1707:
	v_lshlrev_b32_e32 v40, 16, v220
	v_and_b32_e32 v41, 0xffff0000, v220
	v_lshlrev_b32_e32 v42, 16, v221
	v_and_b32_e32 v43, 0xffff0000, v221
	v_lshlrev_b32_e32 v44, 16, v222
	v_and_b32_e32 v45, 0xffff0000, v222
	v_lshlrev_b32_e32 v46, 16, v223
	v_and_b32_e32 v47, 0xffff0000, v223
.LBB0_1708:
	v_pk_add_f32 v[36:37], v[36:37], v[40:41]
	v_mul_f32_e32 v54, v63, v63
	v_pk_add_f32 v[38:39], v[38:39], v[42:43]
	v_pk_add_f32 v[42:43], v[32:33], v[44:45]
	v_mul_f32_e32 v32, v37, v37
	v_fmac_f32_e32 v54, v62, v62
	v_fmac_f32_e32 v32, v36, v36
	v_fmac_f32_e32 v54, v50, v50
	v_fmac_f32_e32 v32, v38, v38
	v_fmac_f32_e32 v54, v51, v51
	v_fmac_f32_e32 v32, v39, v39
	v_fmac_f32_e32 v54, v52, v52
	v_fmac_f32_e32 v32, v42, v42
	v_fmac_f32_e32 v54, v53, v53
	v_pk_add_f32 v[40:41], v[34:35], v[46:47]
	v_fmac_f32_e32 v32, v43, v43
	v_fmac_f32_e32 v54, v48, v48
	v_fmac_f32_e32 v32, v40, v40
	v_fmac_f32_e32 v54, v49, v49
	v_fmac_f32_e32 v32, v41, v41
	v_add_f32_e32 v32, v54, v32
	ds_bpermute_b32 v33, v129, v32
	v_cvt_pk_bf16_f32 v34, v36, v37
	v_cvt_pk_bf16_f32 v35, v38, v39
	v_cvt_pk_bf16_f32 v36, v42, v43
	v_cvt_pk_bf16_f32 v37, v40, v41
	s_waitcnt lgkmcnt(0)
	v_add_f32_e32 v32, v32, v33
	ds_bpermute_b32 v33, v128, v32
	global_store_dwordx4 v[58:59], v[34:37], off offset:256
	s_and_saveexec_b64 s[34:35], s[4:5]
	s_cbranch_execz .LBB0_1710
	s_waitcnt lgkmcnt(0)
	v_add_f32_e32 v34, v32, v33
	v_lshlrev_b64 v[32:33], 6, v[56:57]
	v_lshl_add_u64 v[32:33], s[10:11], 0, v[32:33]
	v_lshl_add_u64 v[32:33], s[28:29], 2, v[32:33]
	s_lshl_b32 s24, s46, 2
	v_lshl_add_u64 v[32:33], v[32:33], 0, s[24:25]
	global_store_dword v[32:33], v34, off

; DI float bf2f(unsigned v) { return __uint_as_float(v << 16); }
;   DI void operator()(const f32x4 (&acc)[2][2][4][2], const pg8::Unit& u, int wr, int wc, int fr_, int fq_) const {
;     ...
;             } else if (EPI == EPI_RESID) {
;               if (n == 0) {
;                 const int f8 = u.pn * 256 + bj * 128 + wc * 32 + 8 * fq;
;                 const f32x4 v1 = acc[ai][bj][m][1];
;                 f32x4 r0, r1;
;                 if (rsrc) {
;                   r0 = *(const f32x4*)(rsrc + (size_t)token * 1024 + f8); r1 = *(const f32x4*)(rsrc + (size_t)token * 1024 + f8 + 4);
;                 } else {
;                   const u32x4 xu = *(const u32x4*)(xr + (size_t)token * 1024 + f8);
;                   r0 = (f32x4){bf2f(xu.x & 0xffffu), bf2f(xu.x >> 16), bf2f(xu.y & 0xffffu), bf2f(xu.y >> 16)};
;                   r1 = (f32x4){bf2f(xu.z & 0xffffu), bf2f(xu.z >> 16), bf2f(xu.w & 0xffffu), bf2f(xu.w >> 16)};
;                 }
;                 r0 += v; r1 += v1;
;                 st_bf8(xr + (size_t)token * 1024 + f8, r0, r1, 1.f);
;                 ssq += r0[0] * r0[0] + r0[1] * r0[1] + r0[2] * r0[2] + r0[3] * r0[3] + r1[0] * r1[0] + r1[1] * r1[1] + r1[2] * r1[2] + r1[3] * r1[3];
;               }
;             } else {
;               if (n == 0) {
;                 const f32x4 v1 = acc[ai][bj][m][1];
;                 u32x4 o4;
;                 { const float t0 = fmaxf(v[0], 0.f) * rinv, t1 = fmaxf(v[1], 0.f) * rinv, t2 = fmaxf(v[2], 0.f) * rinv, t3 = fmaxf(v[3], 0.f) * rinv;
;                   o4.x = pack2(t0 * t0, t1 * t1); o4.y = pack2(t2 * t2, t3 * t3); }
;                 { const float t0 = fmaxf(v1[0], 0.f) * rinv, t1 = fmaxf(v1[1], 0.f) * rinv, t2 = fmaxf(v1[2], 0.f) * rinv, t3 = fmaxf(v1[3], 0.f) * rinv;
;                   o4.z = pack2(t0 * t0, t1 * t1); o4.w = pack2(t2 * t2, t3 * t3); }
;                 *(u32x4*)((u16*)big + (size_t)token * 4096 + u.pn * 256 + bj * 128 + wc * 32 + 8 * fq) = o4;
;               }
;             }
;           }
;         if (EPI == EPI_RESID) {
;           ssq += shx(ssq, 16, t_ & 63);
;           ssq += shx(ssq, 32, t_ & 63);
;           if (fq == 0) ss_out[(size_t)token * 16 + u.pn * 4 + wc] = ssq;
.LBB0_1714:
	v_lshlrev_b64 v[42:43], 11, v[40:41]
	v_lshl_add_u64 v[42:43], s[12:13], 0, v[42:43]
	s_andn2_b64 vcc, exec, s[34:35]
	v_lshl_add_u64 v[42:43], v[148:149], 1, v[42:43]
	s_cbranch_vccnz .Lrw_1644_12
	v_lshlrev_b32_e32 v32, 16, v224
	v_and_b32_e32 v33, 0xffff0000, v224
	v_lshlrev_b32_e32 v34, 16, v225
	v_and_b32_e32 v35, 0xffff0000, v225
	v_lshlrev_b32_e32 v36, 16, v226
	v_and_b32_e32 v37, 0xffff0000, v226
	v_lshlrev_b32_e32 v38, 16, v227
	v_and_b32_e32 v39, 0xffff0000, v227
.LBB0_1716:
	v_pk_add_f32 v[34:35], v[30:31], v[34:35]
	v_pk_add_f32 v[46:47], v[28:29], v[32:33]
	v_pk_add_f32 v[32:33], v[26:27], v[38:39]
	v_pk_add_f32 v[36:37], v[24:25], v[36:37]
	v_cvt_pk_bf16_f32 v24, v46, v47
	v_cvt_pk_bf16_f32 v25, v34, v35
	v_cvt_pk_bf16_f32 v26, v36, v37
	v_cvt_pk_bf16_f32 v27, v32, v33
	s_and_b64 vcc, exec, s[2:3]
	global_store_dwordx4 v[42:43], v[24:27], off
	s_cbranch_vccnz .LBB0_1723
	global_load_dwordx4 v[28:31], v[44:45], off offset:528
	global_load_dwordx4 v[24:27], v[44:45], off offset:512
	s_cbranch_execnz .Lrw_1644_13
.LBB0_1718:
	v_lshlrev_b32_e32 v24, 16, v228
	v_and_b32_e32 v25, 0xffff0000, v228
	v_lshlrev_b32_e32 v26, 16, v229
	v_and_b32_e32 v27, 0xffff0000, v229
	v_lshlrev_b32_e32 v28, 16, v230
	v_and_b32_e32 v29, 0xffff0000, v230
	v_lshlrev_b32_e32 v30, 16, v231
	v_and_b32_e32 v31, 0xffff0000, v231
.LBB0_1719:
	v_pk_add_f32 v[20:21], v[20:21], v[24:25]
	v_mul_f32_e32 v38, v47, v47
	v_pk_add_f32 v[22:23], v[22:23], v[26:27]
	v_pk_add_f32 v[26:27], v[16:17], v[28:29]
	v_mul_f32_e32 v16, v21, v21
	v_fmac_f32_e32 v38, v46, v46
	v_fmac_f32_e32 v16, v20, v20
	v_fmac_f32_e32 v38, v34, v34
	v_fmac_f32_e32 v16, v22, v22
	v_fmac_f32_e32 v38, v35, v35
	v_fmac_f32_e32 v16, v23, v23
	v_fmac_f32_e32 v38, v36, v36
	v_fmac_f32_e32 v16, v26, v26
	v_fmac_f32_e32 v38, v37, v37
	v_pk_add_f32 v[24:25], v[18:19], v[30:31]
	v_fmac_f32_e32 v16, v27, v27
	v_fmac_f32_e32 v38, v32, v32
	v_fmac_f32_e32 v16, v24, v24
	v_fmac_f32_e32 v38, v33, v33
	v_fmac_f32_e32 v16, v25, v25
	v_add_f32_e32 v16, v38, v16
	ds_bpermute_b32 v17, v129, v16
	v_cvt_pk_bf16_f32 v18, v20, v21
	v_cvt_pk_bf16_f32 v19, v22, v23
	v_cvt_pk_bf16_f32 v20, v26, v27
	v_cvt_pk_bf16_f32 v21, v24, v25
	s_waitcnt lgkmcnt(0)
	v_add_f32_e32 v16, v16, v17
	ds_bpermute_b32 v17, v128, v16
	global_store_dwordx4 v[42:43], v[18:21], off offset:256
	s_and_saveexec_b64 s[34:35], s[4:5]
	s_cbranch_execz .LBB0_1721
	s_waitcnt lgkmcnt(0)
	v_add_f32_e32 v18, v16, v17
	v_lshlrev_b64 v[16:17], 6, v[40:41]
	v_lshl_add_u64 v[16:17], s[10:11], 0, v[16:17]
	v_lshl_add_u64 v[16:17], s[28:29], 2, v[16:17]
	s_lshl_b32 s24, s46, 2
	v_lshl_add_u64 v[16:17], v[16:17], 0, s[24:25]
	global_store_dword v[16:17], v18, off

; DI float bf2f(unsigned v) { return __uint_as_float(v << 16); }
;   DI void operator()(const f32x4 (&acc)[2][2][4][2], const pg8::Unit& u, int wr, int wc, int fr_, int fq_) const {
;     ...
;             } else if (EPI == EPI_RESID) {
;               if (n == 0) {
;                 const int f8 = u.pn * 256 + bj * 128 + wc * 32 + 8 * fq;
;                 const f32x4 v1 = acc[ai][bj][m][1];
;                 f32x4 r0, r1;
;                 if (rsrc) {
;                   r0 = *(const f32x4*)(rsrc + (size_t)token * 1024 + f8); r1 = *(const f32x4*)(rsrc + (size_t)token * 1024 + f8 + 4);
;                 } else {
;                   const u32x4 xu = *(const u32x4*)(xr + (size_t)token * 1024 + f8);
;                   r0 = (f32x4){bf2f(xu.x & 0xffffu), bf2f(xu.x >> 16), bf2f(xu.y & 0xffffu), bf2f(xu.y >> 16)};
;                   r1 = (f32x4){bf2f(xu.z & 0xffffu), bf2f(xu.z >> 16), bf2f(xu.w & 0xffffu), bf2f(xu.w >> 16)};
;                 }
;                 r0 += v; r1 += v1;
;                 st_bf8(xr + (size_t)token * 1024 + f8, r0, r1, 1.f);
;                 ssq += r0[0] * r0[0] + r0[1] * r0[1] + r0[2] * r0[2] + r0[3] * r0[3] + r1[0] * r1[0] + r1[1] * r1[1] + r1[2] * r1[2] + r1[3] * r1[3];
;               }
;             } else {
;               if (n == 0) {
;                 const f32x4 v1 = acc[ai][bj][m][1];
;                 u32x4 o4;
;                 { const float t0 = fmaxf(v[0], 0.f) * rinv, t1 = fmaxf(v[1], 0.f) * rinv, t2 = fmaxf(v[2], 0.f) * rinv, t3 = fmaxf(v[3], 0.f) * rinv;
;                   o4.x = pack2(t0 * t0, t1 * t1); o4.y = pack2(t2 * t2, t3 * t3); }
;                 { const float t0 = fmaxf(v1[0], 0.f) * rinv, t1 = fmaxf(v1[1], 0.f) * rinv, t2 = fmaxf(v1[2], 0.f) * rinv, t3 = fmaxf(v1[3], 0.f) * rinv;
;                   o4.z = pack2(t0 * t0, t1 * t1); o4.w = pack2(t2 * t2, t3 * t3); }
;                 *(u32x4*)((u16*)big + (size_t)token * 4096 + u.pn * 256 + bj * 128 + wc * 32 + 8 * fq) = o4;
;               }
;             }
;           }
;         if (EPI == EPI_RESID) {
;           ssq += shx(ssq, 16, t_ & 63);
;           ssq += shx(ssq, 32, t_ & 63);
;           if (fq == 0) ss_out[(size_t)token * 16 + u.pn * 4 + wc] = ssq;
.LBB0_1725:
	v_lshlrev_b64 v[26:27], 11, v[24:25]
	v_lshl_add_u64 v[26:27], s[12:13], 0, v[26:27]
	s_andn2_b64 vcc, exec, s[34:35]
	v_lshl_add_u64 v[26:27], v[148:149], 1, v[26:27]
	s_cbranch_vccnz .Lrw_1644_14
	v_lshlrev_b32_e32 v16, 16, v232
	v_and_b32_e32 v17, 0xffff0000, v232
	v_lshlrev_b32_e32 v18, 16, v233
	v_and_b32_e32 v19, 0xffff0000, v233
	v_lshlrev_b32_e32 v20, 16, v234
	v_and_b32_e32 v21, 0xffff0000, v234
	v_lshlrev_b32_e32 v22, 16, v235
	v_and_b32_e32 v23, 0xffff0000, v235
.LBB0_1727:
	v_pk_add_f32 v[18:19], v[14:15], v[18:19]
	v_pk_add_f32 v[30:31], v[12:13], v[16:17]
	v_pk_add_f32 v[16:17], v[10:11], v[22:23]
	v_pk_add_f32 v[20:21], v[8:9], v[20:21]
	v_cvt_pk_bf16_f32 v8, v30, v31
	v_cvt_pk_bf16_f32 v9, v18, v19
	v_cvt_pk_bf16_f32 v10, v20, v21
	v_cvt_pk_bf16_f32 v11, v16, v17
	s_and_b64 vcc, exec, s[2:3]
	global_store_dwordx4 v[26:27], v[8:11], off
	s_cbranch_vccnz .LBB0_1732
	global_load_dwordx4 v[12:15], v[28:29], off offset:528
	global_load_dwordx4 v[8:11], v[28:29], off offset:512
	s_cbranch_execnz .Lrw_1644_15
.LBB0_1729:
	v_lshlrev_b32_e32 v8, 16, v242
	v_and_b32_e32 v9, 0xffff0000, v242
	v_lshlrev_b32_e32 v10, 16, v243
	v_and_b32_e32 v11, 0xffff0000, v243
	v_lshlrev_b32_e32 v12, 16, v244
	v_and_b32_e32 v13, 0xffff0000, v244
	v_lshlrev_b32_e32 v14, 16, v245
	v_and_b32_e32 v15, 0xffff0000, v245
.LBB0_1730:
	v_pk_add_f32 v[4:5], v[4:5], v[8:9]
	v_mul_f32_e32 v22, v31, v31
	v_pk_add_f32 v[6:7], v[6:7], v[10:11]
	v_pk_add_f32 v[10:11], v[0:1], v[12:13]
	v_mul_f32_e32 v0, v5, v5
	v_fmac_f32_e32 v22, v30, v30
	v_fmac_f32_e32 v0, v4, v4
	v_fmac_f32_e32 v22, v18, v18
	v_fmac_f32_e32 v0, v6, v6
	v_fmac_f32_e32 v22, v19, v19
	v_fmac_f32_e32 v0, v7, v7
	v_fmac_f32_e32 v22, v20, v20
	v_fmac_f32_e32 v0, v10, v10
	v_fmac_f32_e32 v22, v21, v21
	v_pk_add_f32 v[8:9], v[2:3], v[14:15]
	v_fmac_f32_e32 v0, v11, v11
	v_fmac_f32_e32 v22, v16, v16
	v_fmac_f32_e32 v0, v8, v8
	v_fmac_f32_e32 v22, v17, v17
	v_fmac_f32_e32 v0, v9, v9
	v_add_f32_e32 v0, v22, v0
	ds_bpermute_b32 v1, v129, v0
	v_cvt_pk_bf16_f32 v2, v4, v5
	v_cvt_pk_bf16_f32 v3, v6, v7
	v_cvt_pk_bf16_f32 v4, v10, v11
	v_cvt_pk_bf16_f32 v5, v8, v9
	s_waitcnt lgkmcnt(0)
	v_add_f32_e32 v0, v0, v1
	ds_bpermute_b32 v1, v128, v0
	global_store_dwordx4 v[26:27], v[2:5], off offset:256
	s_and_saveexec_b64 s[2:3], s[4:5]
	s_cbranch_execz .LBB0_1636
	s_waitcnt lgkmcnt(0)
	v_add_f32_e32 v2, v0, v1
	v_lshlrev_b64 v[0:1], 6, v[24:25]
	v_lshl_add_u64 v[0:1], s[10:11], 0, v[0:1]
	v_lshl_add_u64 v[0:1], s[28:29], 2, v[0:1]
	s_lshl_b32 s24, s46, 2
	v_lshl_add_u64 v[0:1], v[0:1], 0, s[24:25]
	global_store_dword v[0:1], v2, off
	s_branch .LBB0_1636
